# w2_transposes_moved_from_P0_to_P2_idle_WGs
# speedup vs baseline: 1.0067x; 1.0067x over previous
; #define LAS __attribute__((address_space(3)))
;     __device__ __forceinline__ float* ctl() const { return (float*)(ws + WS_CTL); }
; __global__ void __launch_bounds__(512, 2) fwd_megakernel(Args a) {
;     extern __shared__ __attribute__((aligned(16))) unsigned char lds_raw[];
;     LAS unsigned char* lds = (LAS unsigned char*)lds_raw;
;     cg::grid_group grid = cg::this_grid();
;     const int tid = threadIdx.x, bid = blockIdx.x, G = gridDim.x;
;     const Args& p = a;
;     volatile LAS unsigned* misc = (volatile LAS unsigned*)(lds + LDS_MISC);
;     if (tid < 2) misc[tid] = 0u;
;     __syncthreads();
;     const XcdBarrier bar = xcd_barrier_post((unsigned*)p.ctl() + CW_BAR, misc);
_Z14fwd_megakernel4Args:
	s_mov_b64 s[100:101], s[0:1]
	s_mov_b32 s94, s2
	s_load_dwordx16 s[44:59], s[0:1], 0xc0
	s_load_dword s2, s[0:1], 0x118
	s_load_dwordx4 s[88:91], s[0:1], 0x100
	s_load_dwordx2 s[96:97], s[0:1], 0x110
	s_add_u32 s4, s0, 0x110
	v_and_b32_e32 v192, 0x3ff, v0
	s_addc_u32 s5, s1, 0
	v_cmp_gt_u32_e32 vcc, 2, v192
	s_waitcnt lgkmcnt(0)
	v_writelane_b32 v242, s2, 0
	s_and_saveexec_b64 s[2:3], vcc
	v_lshl_add_u32 v1, v192, 2, 0
	v_add_u32_e32 v1, 0x21fc0, v1
	v_mov_b32_e32 v2, 0
	ds_write_b32 v1, v2
	s_or_b64 exec, exec, s[2:3]
	s_waitcnt lgkmcnt(0)
	s_barrier
	s_add_u32 s92, s58, 0x50000
	s_getreg_b32 s2, hwreg(HW_REG_XCC_ID, 0, 4)
	s_addc_u32 s93, s59, 0
	s_and_b32 s84, s2, 15
	v_cmp_eq_u32_e64 s[6:7], 0, v192
	s_mov_b64 s[2:3], exec
	s_nop 0
	v_writelane_b32 v242, s6, 1
	s_nop 1
	v_writelane_b32 v242, s7, 2
	s_and_b64 s[6:7], s[2:3], s[6:7]
	s_mov_b64 exec, s[6:7]
	s_cbranch_execz .LBB0_5
	s_mov_b64 s[6:7], exec
	v_mbcnt_lo_u32_b32 v1, s6, 0
	v_mbcnt_hi_u32_b32 v1, s7, v1
	v_cmp_eq_u32_e32 vcc, 0, v1
	s_and_b64 s[8:9], exec, vcc
	s_mov_b64 exec, s[8:9]
	s_cbranch_execz .LBB0_5
	s_lshl_b32 s8, s84, 8
	s_bcnt1_i32_b64 s6, s[6:7]
	v_mov_b32_e32 v1, s8
	v_mov_b32_e32 v2, s6
	global_atomic_add v1, v2, s[92:93] offset:1024

;     __device__ __forceinline__ float* ctl() const { return (float*)(ws + WS_CTL); }
;     __device__ __forceinline__ bf16_t* Win_t() const { return (bf16_t*)(ws + WS_WIN); }
;     __device__ __forceinline__ bf16_t* Wkv_t() const { return (bf16_t*)(ws + WS_WKV); }
;     __device__ __forceinline__ bf16_t* Wout_t() const { return (bf16_t*)(ws + WS_WOUT); }
;     __device__ __forceinline__ bf16_t* Wq_t() const { return (bf16_t*)(ws + WS_WQ); }
;     __device__ __forceinline__ bf16_t* Wo_t() const { return (bf16_t*)(ws + WS_WO); }
;     __device__ __forceinline__ bf16_t* W1_t() const { return (bf16_t*)(ws + WS_W1); }
;     __device__ __forceinline__ bf16_t* W2_t() const { return (bf16_t*)(ws + WS_W2); }
; __device__ __forceinline__ void p0_prologue(const Args& p, LAS unsigned char* lds, int G, int bid, int tid) {
;     ...
;     for (int it = gw; it < NITEMS; it += NGW) {
;         int r = it;
;         if (r < I_IN) { tr_item<1>(p.w_in(), DIN, p.Win_t(), DM, 0, scr, r / 48, r % 48, lane, nullptr, nullptr, nullptr, nullptr); continue; } r -= I_IN;
;         if (r < I_K) { tr_item<0>(p.xk_w(), DM, p.Wkv_t(), DM, 0, scr, r / 32, r % 32, lane, nullptr, nullptr, nullptr, nullptr); continue; } r -= I_K;
;         if (r < I_V) { tr_item<0>(p.xv_w(), DM, p.Wkv_t(), DM, DM, scr, r / 32, r % 32, lane, nullptr, nullptr, nullptr, nullptr); continue; } r -= I_V;
;         if (r < I_OUT) { tr_item<0>(p.w_out(), DM, p.Wout_t(), DM, 0, scr, r / 32, r % 32, lane, nullptr, nullptr, nullptr, nullptr); continue; } r -= I_OUT;
;         if (r < I_Q) { tr_item<2>(p.xq_w(), DM, p.Wq_t(), DM, 0, scr, r / 32, r % 32, lane, p.ln1_g(), p.ln1_b(), p.ctl() + CF_C1Q, p.ctl() + CF_C2Q); continue; } r -= I_Q;
;         if (r < I_O) { tr_item<0>(p.xo_w(), DM, p.Wo_t(), DM, 0, scr, r / 32, r % 32, lane, nullptr, nullptr, nullptr, nullptr); continue; } r -= I_O;
;         if (r < I_1) { tr_item<2>(p.w1(), DFF, p.W1_t(), DM, 0, scr, r / 128, r % 128, lane, p.ln2_g(), p.ln2_b(), p.ctl() + CF_C1H, p.ctl() + CF_C2H); continue; } r -= I_1;
;         tr_item<0>(p.w2(), DM, p.W2_t(), DFF, 0, scr, r / 32, r % 32, lane, nullptr, nullptr, nullptr, nullptr);
;     }
.LBB0_23:
	v_lshrrev_b32_e32 v42, 6, v192
	v_lshl_add_u32 v41, s94, 3, v42
	s_movk_i32 s0, 0x1400
	v_cmp_gt_i32_e32 vcc, s0, v41
	s_and_saveexec_b64 s[0:1], vcc
	s_cbranch_execz .LBB0_74
	v_and_b32_e32 v2, 31, v192
	v_lshlrev_b32_e32 v30, 2, v2
	v_lshlrev_b32_e32 v2, 3, v192
	v_bfe_u32 v59, v192, 3, 3
	v_and_b32_e32 v18, 56, v2
	v_and_b32_e32 v0, 63, v192
	v_lshl_add_u32 v1, v42, 14, 0
	v_mul_u32_u24_e32 v2, 0x84, v18
	v_lshlrev_b32_e32 v3, 2, v59
	v_add_u32_e32 v57, v1, v30
	v_add3_u32 v60, v1, v2, v3
	v_mov_b32_e32 v1, 0x4a000
	v_mov_b32_e32 v2, 0x46000
	v_cmp_gt_u32_e32 vcc, 32, v0
	v_readlane_b32 s4, v242, 3
	v_bfe_u32 v56, v192, 5, 1
	v_cndmask_b32_e32 v0, v1, v2, vcc
	v_mov_b32_e32 v1, 0
	s_movk_i32 s2, 0x84
	v_mov_b32_e32 v31, v1
	v_readlane_b32 s17, v242, 16
	v_readlane_b32 s19, v242, 18
	v_mad_u32_u24 v58, v56, s2, v57
	v_readlane_b32 s16, v242, 15
	v_readlane_b32 s18, v242, 17
	s_waitcnt lgkmcnt(0)
	v_lshl_add_u64 v[10:11], s[74:75], 0, v[30:31]
	s_mov_b32 s2, s84
	v_readlane_b32 s72, v242, 19
	v_mov_b32_e32 v20, s19
	v_mov_b32_e32 v21, s17
	v_and_b32_e32 v24, 7, v192
	v_readlane_b32 s84, v242, 31
	v_lshlrev_b32_e32 v18, 1, v18
	v_mov_b32_e32 v19, v1
	v_cndmask_b32_e32 v21, v20, v21, vcc
	v_mov_b32_e32 v20, s18
	v_mov_b32_e32 v22, s16
	s_mov_b32 s84, s2
	v_lshl_add_u64 v[38:39], s[58:59], 0, v[18:19]
	s_mov_b64 s[2:3], 0x1700000
	v_cndmask_b32_e32 v20, v20, v22, vcc
	v_lshl_add_u64 v[22:23], s[58:59], 0, v[0:1]
	v_lshlrev_b32_e32 v0, 4, v24
	v_mov_b32_e32 v2, 0x45000
	v_mov_b32_e32 v3, 0x44000
	v_lshl_add_u64 v[18:19], v[38:39], 0, s[2:3]
	v_lshl_add_u64 v[34:35], s[58:59], 0, v[0:1]
	s_mov_b64 s[2:3], 0xf00000
	v_lshlrev_b32_e32 v64, 3, v24
	v_cndmask_b32_e32 v32, v2, v3, vcc
	v_mov_b32_e32 v33, v1
	v_lshl_add_u64 v[24:25], v[34:35], 0, s[2:3]
	s_mov_b64 s[2:3], 0xd00000
	v_readlane_b32 s5, v242, 4
	v_readlane_b32 s7, v242, 6
	v_readlane_b32 s8, v242, 7
	v_readlane_b32 s9, v242, 8
	v_readlane_b32 s10, v242, 9
	v_readlane_b32 s11, v242, 10
	v_readlane_b32 s12, v242, 11
	v_readlane_b32 s13, v242, 12
	v_readlane_b32 s14, v242, 13
	v_readlane_b32 s15, v242, 14
	v_readlane_b32 s86, v242, 33
	v_readlane_b32 s87, v242, 34
	v_lshl_add_u64 v[26:27], v[38:39], 0, s[2:3]
	v_lshl_add_u64 v[32:33], s[58:59], 0, v[32:33]
	s_mov_b64 s[2:3], 0xb00000
	v_lshl_add_u64 v[2:3], s[48:49], 0, v[30:31]
	v_lshl_add_u64 v[4:5], s[44:45], 0, v[30:31]
	v_readlane_b32 s6, v242, 5
	v_lshl_add_u64 v[6:7], s[14:15], 0, v[30:31]
	v_lshl_add_u64 v[8:9], s[8:9], 0, v[30:31]
	v_lshl_add_u64 v[12:13], s[12:13], 0, v[30:31]
	v_lshl_add_u64 v[14:15], s[10:11], 0, v[30:31]
	v_lshl_add_u64 v[16:17], s[86:87], 0, v[30:31]
	v_lshl_add_u64 v[22:23], v[22:23], 0, v[30:31]
	v_mov_b32_e32 v0, s7
	v_mov_b32_e32 v28, s5
	v_lshl_add_u64 v[30:31], v[32:33], 0, v[30:31]
	v_lshl_add_u64 v[32:33], v[34:35], 0, s[2:3]
	s_mov_b64 s[2:3], 0x900000
	v_cndmask_b32_e32 v29, v0, v28, vcc
	v_mov_b32_e32 v0, s6
	v_mov_b32_e32 v28, s4
	v_lshl_add_u64 v[34:35], v[38:39], 0, s[2:3]
	s_mov_b64 s[2:3], 0x500000
	v_cndmask_b32_e32 v28, v0, v28, vcc
	v_lshl_add_u64 v[36:37], v[38:39], 0, s[2:3]
	s_mov_b64 s[2:3], 0x200000
	v_lshlrev_b32_e32 v0, 1, v42
	s_lshl_b32 s20, s96, 3
	v_or_b32_e32 v61, 8, v59
	v_or_b32_e32 v62, 16, v59
	v_or_b32_e32 v63, 24, v59
	v_bitop3_b32 v65, v59, 15, 24 bitop3:0xc8
	v_lshl_add_u64 v[38:39], v[38:39], 0, s[2:3]
	v_add_u32_e32 v40, 0xfffff400, v41
	v_lshl_add_u32 v66, s94, 4, v0
	s_lshl_b32 s21, s96, 4
	v_mov_b32_e32 v67, 0x7ffffc00
	s_mov_b32 s22, 0x7fffffc0
	s_mov_b32 s23, 0x8000
	s_mov_b32 s24, 0x10000
	s_mov_b32 s25, 0x18000
	s_mov_b32 s26, 0x20000
	s_mov_b32 s27, 0x28000
	s_mov_b32 s28, 0x30000
	s_mov_b32 s29, 0x38000
	s_mov_b32 s30, 0xc8000
	s_mov_b32 s31, 0xd0000
	s_mov_b32 s33, 0xd8000
	s_mov_b32 s34, 0xe0000
	s_mov_b32 s35, 0xe8000
	s_mov_b32 s36, 0xf0000
	s_mov_b32 s37, 0xf8000
	s_movk_i32 s38, 0x400
	s_mov_b32 s39, 0x2aaaaaab
	s_movk_i32 s40, 0x1800
	s_movk_i32 s41, 0x1ff
	s_mov_b32 s42, 0x7fffffe0
	s_movk_i32 s43, 0xffe0
	s_movk_i32 s44, 0x13ff
	s_mov_b64 s[2:3], 0
	v_readlane_b32 s73, v242, 20
	v_readlane_b32 s74, v242, 21
	v_readlane_b32 s75, v242, 22
	v_readlane_b32 s76, v242, 23
	v_readlane_b32 s77, v242, 24
	v_readlane_b32 s78, v242, 25
	v_readlane_b32 s79, v242, 26
	v_readlane_b32 s80, v242, 27
	v_readlane_b32 s81, v242, 28
	v_readlane_b32 s82, v242, 29
	v_readlane_b32 s83, v242, 30
	v_readlane_b32 s85, v242, 32
	s_branch .LBB0_27

; #define LAS __attribute__((address_space(3)))
; __device__ __forceinline__ unsigned pk2(float lo, float hi) { f32x2v v = {lo, hi}; b16x2v b = __builtin_convertvector(v, b16x2v); return __builtin_bit_cast(unsigned, b); }
; template <int MODE>
; __device__ __forceinline__ void tr_item(const float* __restrict__ W, int N, bf16_t* WT, int ldk, int row_off, LAS float* scr, int kb, int nb, int lane,
;                                         const float* g, const float* b, float* c1, float* c2) {
;     const int k0 = 64 * kb, n0 = 32 * nb;
;     float tv[32];
; #pragma unroll
;     for (int i = 0; i < 32; ++i) tv[i] = __builtin_nontemporal_load(W + (size_t)(k0 + 2 * i + (lane >> 5)) * N + n0 + (lane & 31));
; #pragma unroll
;     for (int i = 0; i < 32; ++i) scr[(2 * i + (lane >> 5)) * 33 + (lane & 31)] = tv[i];
;     asm volatile("s_waitcnt lgkmcnt(0)" ::: "memory");
;     if (MODE == 2) {
;         const float* vec = (lane < 32) ? g : b; float s = 0.f;
; #pragma unroll 8
;         for (int k = 0; k < 64; ++k) s += vec[k0 + k] * scr[k * 33 + (lane & 31)];
;         atomicAdd(((lane < 32) ? c1 : c2) + n0 + (lane & 31), s);
;     }
;     const int c = lane & 7;
;     float gs[8];
; #pragma unroll
;     for (int i = 0; i < 8; ++i) gs[i] = (MODE == 2) ? g[k0 + 8 * c + i] : 1.0f;
; #pragma unroll
;     for (int j = 0; j < 4; ++j) { const int n = (lane >> 3) + 8 * j; const LAS float* s = scr + (8 * c) * 33 + n;
;         u32x4 o; o.x = pk2(s[0 * 33] * gs[0], s[1 * 33] * gs[1]); o.y = pk2(s[2 * 33] * gs[2], s[3 * 33] * gs[3]); o.z = pk2(s[4 * 33] * gs[4], s[5 * 33] * gs[5]); o.w = pk2(s[6 * 33] * gs[6], s[7 * 33] * gs[7]);
;         const int dr = (MODE == 1) ? win_dest(n0 + n) : (n0 + n);
;         *(u32x4*)(WT + (size_t)(row_off + dr) * ldk + k0 + 8 * c) = o; }
; __device__ __forceinline__ void p2_mixer(const Args& p, int G, int bid, int tid) {
;     ...
;     const int vcu = (G % 8 == 0) ? (bid % 8) * (G / 8) + bid / 8 : bid;
.LBB0_619:
	s_and_b32 s0, s96, 7
	s_cmp_lg_u32 s0, 0
	s_mov_b32 s1, s94
	s_cbranch_scc1 .Ltr2_vcu
	s_and_b32 s0, s94, 7
	s_lshr_b32 s1, s96, 3
	s_mul_i32 s0, s0, s1
	s_lshr_b32 s1, s94, 3
	s_add_u32 s1, s0, s1
.Ltr2_vcu:
	s_cmp_lt_u32 s1, 64
	s_cbranch_scc1 .Ltr2_skip
	s_sub_u32 s1, s1, 64
	v_lshrrev_b32_e32 v32, 6, v192
	v_and_b32_e32 v33, 63, v192
	v_readfirstlane_b32 s0, v32
	s_load_dwordx2 s[8:9], s[100:101], 0xd0
	s_nop 3
	s_lshl_b32 s1, s1, 3
	s_add_u32 s10, s1, s0
	s_sub_u32 s11, s96, 64
	s_lshl_b32 s11, s11, 3
	s_lshl_b32 s0, s0, 14
	v_lshrrev_b32_e32 v38, 5, v33
	v_and_b32_e32 v39, 31, v33
	v_lshlrev_b32_e32 v34, 12, v38
	v_lshl_add_u32 v34, v39, 2, v34
	v_mul_u32_u24_e32 v35, 0x84, v38
	v_lshl_add_u32 v35, v39, 2, v35
	v_add_u32_e32 v35, s0, v35
	v_and_b32_e32 v38, 7, v33
	v_lshrrev_b32_e32 v39, 3, v33
	v_mul_u32_u24_e32 v36, 0x420, v38
	v_lshl_add_u32 v36, v39, 2, v36
	v_add_u32_e32 v36, s0, v36
	v_lshlrev_b32_e32 v37, 13, v39
	v_lshl_add_u32 v37, v38, 4, v37
	s_waitcnt lgkmcnt(0)
; #define LAS __attribute__((address_space(3)))
; __device__ __forceinline__ unsigned pk2(float lo, float hi) { f32x2v v = {lo, hi}; b16x2v b = __builtin_convertvector(v, b16x2v); return __builtin_bit_cast(unsigned, b); }
; template <int MODE>
; __device__ __forceinline__ void tr_item(const float* __restrict__ W, int N, bf16_t* WT, int ldk, int row_off, LAS float* scr, int kb, int nb, int lane,
;                                         const float* g, const float* b, float* c1, float* c2) {
;     const int k0 = 64 * kb, n0 = 32 * nb;
;     float tv[32];
; #pragma unroll
;     for (int i = 0; i < 32; ++i) tv[i] = __builtin_nontemporal_load(W + (size_t)(k0 + 2 * i + (lane >> 5)) * N + n0 + (lane & 31));
; #pragma unroll
;     for (int i = 0; i < 32; ++i) scr[(2 * i + (lane >> 5)) * 33 + (lane & 31)] = tv[i];
;     asm volatile("s_waitcnt lgkmcnt(0)" ::: "memory");
;     if (MODE == 2) {
;         const float* vec = (lane < 32) ? g : b; float s = 0.f;
; #pragma unroll 8
;         for (int k = 0; k < 64; ++k) s += vec[k0 + k] * scr[k * 33 + (lane & 31)];
;         atomicAdd(((lane < 32) ? c1 : c2) + n0 + (lane & 31), s);
;     }
;     const int c = lane & 7;
;     float gs[8];
; #pragma unroll
;     for (int i = 0; i < 8; ++i) gs[i] = (MODE == 2) ? g[k0 + 8 * c + i] : 1.0f;
; #pragma unroll
;     for (int j = 0; j < 4; ++j) { const int n = (lane >> 3) + 8 * j; const LAS float* s = scr + (8 * c) * 33 + n;
;         u32x4 o; o.x = pk2(s[0 * 33] * gs[0], s[1 * 33] * gs[1]); o.y = pk2(s[2 * 33] * gs[2], s[3 * 33] * gs[3]); o.z = pk2(s[4 * 33] * gs[4], s[5 * 33] * gs[5]); o.w = pk2(s[6 * 33] * gs[6], s[7 * 33] * gs[7]);
;         const int dr = (MODE == 1) ? win_dest(n0 + n) : (n0 + n);
;         *(u32x4*)(WT + (size_t)(row_off + dr) * ldk + k0 + 8 * c) = o; }
;     asm volatile("s_waitcnt lgkmcnt(0)" ::: "memory");
.Ltr2_loop:
	s_cmp_ge_u32 s10, 0x800
	s_cbranch_scc1 .Ltr2_skip
	s_lshr_b32 s0, s10, 5
	s_and_b32 s1, s10, 31
	s_mul_i32 s12, s0, 0x40000
	s_lshl_b32 s13, s1, 7
	s_add_u32 s12, s12, s13
	s_add_u32 s12, s8, s12
	s_addc_u32 s13, s9, 0
	global_load_dword v40, v34, s[12:13] nt
	s_add_u32 s12, s12, 0x2000
	s_addc_u32 s13, s13, 0
	global_load_dword v41, v34, s[12:13] nt
	s_add_u32 s12, s12, 0x2000
	s_addc_u32 s13, s13, 0
	global_load_dword v42, v34, s[12:13] nt
	s_add_u32 s12, s12, 0x2000
	s_addc_u32 s13, s13, 0
	global_load_dword v43, v34, s[12:13] nt
	s_add_u32 s12, s12, 0x2000
	s_addc_u32 s13, s13, 0
	global_load_dword v44, v34, s[12:13] nt
	s_add_u32 s12, s12, 0x2000
	s_addc_u32 s13, s13, 0
	global_load_dword v45, v34, s[12:13] nt
	s_add_u32 s12, s12, 0x2000
	s_addc_u32 s13, s13, 0
	global_load_dword v46, v34, s[12:13] nt
	s_add_u32 s12, s12, 0x2000
	s_addc_u32 s13, s13, 0
	global_load_dword v47, v34, s[12:13] nt
	s_add_u32 s12, s12, 0x2000
	s_addc_u32 s13, s13, 0
	global_load_dword v48, v34, s[12:13] nt
	s_add_u32 s12, s12, 0x2000
	s_addc_u32 s13, s13, 0
	global_load_dword v49, v34, s[12:13] nt
	s_add_u32 s12, s12, 0x2000
	s_addc_u32 s13, s13, 0
	global_load_dword v50, v34, s[12:13] nt
	s_add_u32 s12, s12, 0x2000
	s_addc_u32 s13, s13, 0
	global_load_dword v51, v34, s[12:13] nt
	s_add_u32 s12, s12, 0x2000
	s_addc_u32 s13, s13, 0
	global_load_dword v52, v34, s[12:13] nt
	s_add_u32 s12, s12, 0x2000
	s_addc_u32 s13, s13, 0
	global_load_dword v53, v34, s[12:13] nt
	s_add_u32 s12, s12, 0x2000
	s_addc_u32 s13, s13, 0
	global_load_dword v54, v34, s[12:13] nt
	s_add_u32 s12, s12, 0x2000
	s_addc_u32 s13, s13, 0
	global_load_dword v55, v34, s[12:13] nt
	s_add_u32 s12, s12, 0x2000
	s_addc_u32 s13, s13, 0
	global_load_dword v56, v34, s[12:13] nt
	s_add_u32 s12, s12, 0x2000
	s_addc_u32 s13, s13, 0
	global_load_dword v57, v34, s[12:13] nt
	s_add_u32 s12, s12, 0x2000
	s_addc_u32 s13, s13, 0
	global_load_dword v58, v34, s[12:13] nt
	s_add_u32 s12, s12, 0x2000
	s_addc_u32 s13, s13, 0
	global_load_dword v59, v34, s[12:13] nt
	s_add_u32 s12, s12, 0x2000
	s_addc_u32 s13, s13, 0
	global_load_dword v60, v34, s[12:13] nt
	s_add_u32 s12, s12, 0x2000
	s_addc_u32 s13, s13, 0
	global_load_dword v61, v34, s[12:13] nt
	s_add_u32 s12, s12, 0x2000
	s_addc_u32 s13, s13, 0
	global_load_dword v62, v34, s[12:13] nt
	s_add_u32 s12, s12, 0x2000
	s_addc_u32 s13, s13, 0
	global_load_dword v63, v34, s[12:13] nt
	s_add_u32 s12, s12, 0x2000
	s_addc_u32 s13, s13, 0
	global_load_dword v64, v34, s[12:13] nt
	s_add_u32 s12, s12, 0x2000
	s_addc_u32 s13, s13, 0
	global_load_dword v65, v34, s[12:13] nt
	s_add_u32 s12, s12, 0x2000
	s_addc_u32 s13, s13, 0
	global_load_dword v66, v34, s[12:13] nt
	s_add_u32 s12, s12, 0x2000
	s_addc_u32 s13, s13, 0
	global_load_dword v67, v34, s[12:13] nt
	s_add_u32 s12, s12, 0x2000
	s_addc_u32 s13, s13, 0
	global_load_dword v68, v34, s[12:13] nt
	s_add_u32 s12, s12, 0x2000
	s_addc_u32 s13, s13, 0
	global_load_dword v69, v34, s[12:13] nt
	s_add_u32 s12, s12, 0x2000
	s_addc_u32 s13, s13, 0
	global_load_dword v70, v34, s[12:13] nt
	s_add_u32 s12, s12, 0x2000
	s_addc_u32 s13, s13, 0
	global_load_dword v71, v34, s[12:13] nt
	s_mul_i32 s12, s1, 0x40000
	s_lshl_b32 s13, s0, 7
	s_add_u32 s12, s12, s13
	s_add_u32 s12, s12, 0x1700000
	s_add_u32 s12, s58, s12
	s_addc_u32 s13, s59, 0
	s_waitcnt vmcnt(31)
	ds_write_b32 v35, v40
	s_waitcnt vmcnt(30)
	ds_write_b32 v35, v41 offset:264
	s_waitcnt vmcnt(29)
	ds_write_b32 v35, v42 offset:528
	s_waitcnt vmcnt(28)
	ds_write_b32 v35, v43 offset:792
	s_waitcnt vmcnt(27)
	ds_write_b32 v35, v44 offset:1056
	s_waitcnt vmcnt(26)
	ds_write_b32 v35, v45 offset:1320
	s_waitcnt vmcnt(25)
	ds_write_b32 v35, v46 offset:1584
	s_waitcnt vmcnt(24)
	ds_write_b32 v35, v47 offset:1848
	s_waitcnt vmcnt(23)
	ds_write_b32 v35, v48 offset:2112
	s_waitcnt vmcnt(22)
	ds_write_b32 v35, v49 offset:2376
	s_waitcnt vmcnt(21)
	ds_write_b32 v35, v50 offset:2640
	s_waitcnt vmcnt(20)
	ds_write_b32 v35, v51 offset:2904
	s_waitcnt vmcnt(19)
	ds_write_b32 v35, v52 offset:3168
	s_waitcnt vmcnt(18)
	ds_write_b32 v35, v53 offset:3432
	s_waitcnt vmcnt(17)
	ds_write_b32 v35, v54 offset:3696
	s_waitcnt vmcnt(16)
	ds_write_b32 v35, v55 offset:3960
	s_waitcnt vmcnt(15)
	ds_write_b32 v35, v56 offset:4224
	s_waitcnt vmcnt(14)
	ds_write_b32 v35, v57 offset:4488
	s_waitcnt vmcnt(13)
	ds_write_b32 v35, v58 offset:4752
	s_waitcnt vmcnt(12)
	ds_write_b32 v35, v59 offset:5016
	s_waitcnt vmcnt(11)
	ds_write_b32 v35, v60 offset:5280
	s_waitcnt vmcnt(10)
	ds_write_b32 v35, v61 offset:5544
	s_waitcnt vmcnt(9)
	ds_write_b32 v35, v62 offset:5808
	s_waitcnt vmcnt(8)
	ds_write_b32 v35, v63 offset:6072
	s_waitcnt vmcnt(7)
	ds_write_b32 v35, v64 offset:6336
	s_waitcnt vmcnt(6)
	ds_write_b32 v35, v65 offset:6600
	s_waitcnt vmcnt(5)
	ds_write_b32 v35, v66 offset:6864
	s_waitcnt vmcnt(4)
	ds_write_b32 v35, v67 offset:7128
	s_waitcnt vmcnt(3)
	ds_write_b32 v35, v68 offset:7392
	s_waitcnt vmcnt(2)
	ds_write_b32 v35, v69 offset:7656
	s_waitcnt vmcnt(1)
	ds_write_b32 v35, v70 offset:7920
	s_waitcnt vmcnt(0)
	ds_write_b32 v35, v71 offset:8184
	s_waitcnt lgkmcnt(0)
	ds_read2_b32 v[72:73], v36 offset1:33
	ds_read2_b32 v[74:75], v36 offset0:66 offset1:99
	ds_read2_b32 v[76:77], v36 offset0:132 offset1:165
	ds_read2_b32 v[78:79], v36 offset0:198 offset1:231
	s_waitcnt lgkmcnt(0)
	v_cvt_pk_bf16_f32 v80, v72, v73
	v_cvt_pk_bf16_f32 v81, v74, v75
	v_cvt_pk_bf16_f32 v82, v76, v77
	v_cvt_pk_bf16_f32 v83, v78, v79
	global_store_dwordx4 v37, v[80:83], s[12:13]
	s_add_u32 s12, s12, 0x10000
	s_addc_u32 s13, s13, 0
	ds_read2_b32 v[72:73], v36 offset0:8 offset1:41
	ds_read2_b32 v[74:75], v36 offset0:74 offset1:107
	ds_read2_b32 v[76:77], v36 offset0:140 offset1:173
	ds_read2_b32 v[78:79], v36 offset0:206 offset1:239
	s_waitcnt lgkmcnt(0)
	v_cvt_pk_bf16_f32 v80, v72, v73
	v_cvt_pk_bf16_f32 v81, v74, v75
	v_cvt_pk_bf16_f32 v82, v76, v77
	v_cvt_pk_bf16_f32 v83, v78, v79
	global_store_dwordx4 v37, v[80:83], s[12:13]
	s_add_u32 s12, s12, 0x10000
	s_addc_u32 s13, s13, 0
	ds_read2_b32 v[72:73], v36 offset0:16 offset1:49
	ds_read2_b32 v[74:75], v36 offset0:82 offset1:115
	ds_read2_b32 v[76:77], v36 offset0:148 offset1:181
	ds_read2_b32 v[78:79], v36 offset0:214 offset1:247
	s_waitcnt lgkmcnt(0)
	v_cvt_pk_bf16_f32 v80, v72, v73
	v_cvt_pk_bf16_f32 v81, v74, v75
	v_cvt_pk_bf16_f32 v82, v76, v77
	v_cvt_pk_bf16_f32 v83, v78, v79
	global_store_dwordx4 v37, v[80:83], s[12:13]
	s_add_u32 s12, s12, 0x10000
	s_addc_u32 s13, s13, 0
	ds_read2_b32 v[72:73], v36 offset0:24 offset1:57
	ds_read2_b32 v[74:75], v36 offset0:90 offset1:123
	ds_read2_b32 v[76:77], v36 offset0:156 offset1:189
	ds_read2_b32 v[78:79], v36 offset0:222 offset1:255
	s_waitcnt lgkmcnt(0)
	v_cvt_pk_bf16_f32 v80, v72, v73
	v_cvt_pk_bf16_f32 v81, v74, v75
	v_cvt_pk_bf16_f32 v82, v76, v77
	v_cvt_pk_bf16_f32 v83, v78, v79
	global_store_dwordx4 v37, v[80:83], s[12:13]
	s_add_u32 s10, s10, s11
	s_branch .Ltr2_loop
